# v1 + NA attention mask/bias reads batched (16 serialized exec-masked ds_read_b32 -> 2x8 unconditional reads + cndmask)
# baseline (speedup 1.0000x reference)
.LBB0_321:
	v_mov_b32_e32 v0, v203
	v_mov_b32_e32 v1, v200
	v_lshlrev_b32_e32 v176, 2, v216
	v_add_u32_e32 v2, -4, v0
	v_min_i32_e32 v2, s76, v2
	v_cmp_lt_i32_e32 vcc, 3, v0
	v_xad_u32 v0, v0, -1, s23
	v_med3_i32 v3, v1, 8, 56
	v_cndmask_b32_e32 v2, 0, v2, vcc
	v_cmp_gt_i32_e32 vcc, s23, v2
	v_add_u32_e32 v2, 8, v2
	v_min_i32_e32 v2, s75, v2
	v_med3_i32 v0, v0, -7, 7
	v_sub_u32_e32 v1, v206, v1
	v_add_u32_e32 v8, -8, v3
	v_cmp_le_i32_e64 s[6:7], s23, v2
	v_lshl_add_u32 v0, v0, 9, s57
	v_lshlrev_b32_e32 v1, 2, v1
	v_add3_u32 v9, v0, v1, v176
	ds_read_b32 v234, v9 offset:3836
	ds_read_b32 v235, v9 offset:3840
	ds_read_b32 v236, v9 offset:3844
	ds_read_b32 v237, v9 offset:3848
	ds_read_b32 v238, v9 offset:3868
	ds_read_b32 v239, v9 offset:3872
	ds_read_b32 v240, v9 offset:3876
	ds_read_b32 v241, v9 offset:3880
	v_sub_u32_e32 v0, v207, v8
	s_and_b64 vcc, s[6:7], vcc
	v_cndmask_b32_e32 v10, v196, v0, vcc
	v_cmp_gt_u32_e64 s[6:7], 16, v10
	v_mov_b32_e32 v0, 0xf149f2ca
	v_mov_b32_e32 v1, 0xf149f2ca
	s_waitcnt lgkmcnt(0)
	v_add_f32_e32 v234, v128, v234
	s_nop 0
	v_cndmask_b32_e64 v1, v1, v234, s[6:7]
	v_add_u32_e32 v2, 1, v10
	v_cmp_gt_u32_e64 s[6:7], 16, v2
	v_add_f32_e32 v235, v129, v235
	s_nop 0
	v_cndmask_b32_e64 v0, v0, v235, s[6:7]
	v_add_u32_e32 v2, 2, v10
	v_cmp_gt_u32_e64 s[6:7], 16, v2
	v_mov_b32_e32 v2, 0xf149f2ca
	v_mov_b32_e32 v3, 0xf149f2ca
	v_add_f32_e32 v236, v130, v236
	s_nop 0
	v_cndmask_b32_e64 v3, v3, v236, s[6:7]
	v_add_u32_e32 v4, 3, v10
	v_cmp_gt_u32_e64 s[6:7], 16, v4
	v_add_f32_e32 v237, v131, v237
	s_nop 0
	v_cndmask_b32_e64 v2, v2, v237, s[6:7]
	v_add_u32_e32 v4, 8, v10
	v_cmp_gt_u32_e64 s[6:7], 16, v4
	v_mov_b32_e32 v4, 0xf149f2ca
	v_mov_b32_e32 v5, 0xf149f2ca
	v_add_f32_e32 v238, v132, v238
	s_nop 0
	v_cndmask_b32_e64 v5, v5, v238, s[6:7]
	v_add_u32_e32 v6, 9, v10
	v_cmp_gt_u32_e64 s[6:7], 16, v6
	v_add_f32_e32 v239, v133, v239
	s_nop 0
	v_cndmask_b32_e64 v4, v4, v239, s[6:7]
	v_add_u32_e32 v6, 10, v10
	v_cmp_gt_u32_e64 s[6:7], 16, v6
	v_mov_b32_e32 v6, 0xf149f2ca
	v_mov_b32_e32 v7, 0xf149f2ca
	v_add_f32_e32 v240, v134, v240
	s_nop 0
	v_cndmask_b32_e64 v7, v7, v240, s[6:7]
	v_add_u32_e32 v10, 11, v10
	v_cmp_gt_u32_e64 s[6:7], 16, v10
	v_add_f32_e32 v241, v135, v241
	s_nop 0
	v_cndmask_b32_e64 v6, v6, v241, s[6:7]
	v_sub_u32_e32 v8, v205, v8
	v_cndmask_b32_e32 v17, v196, v8, vcc
	v_lshl_add_u32 v16, v218, 2, v9
	ds_read_b32 v234, v16 offset:3836
	ds_read_b32 v235, v16 offset:3840
	ds_read_b32 v236, v16 offset:3844
	ds_read_b32 v237, v16 offset:3848
	ds_read_b32 v238, v16 offset:3868
	ds_read_b32 v239, v16 offset:3872
	ds_read_b32 v240, v16 offset:3876
	ds_read_b32 v241, v16 offset:3880
	v_cmp_gt_u32_e32 vcc, 16, v17
	v_mov_b32_e32 v8, 0xf149f2ca
	v_mov_b32_e32 v9, 0xf149f2ca
	s_waitcnt lgkmcnt(0)
	v_add_f32_e32 v234, v136, v234
	s_nop 0
	v_cndmask_b32_e32 v9, v9, v234, vcc
	v_add_u32_e32 v10, 1, v17
	v_cmp_gt_u32_e32 vcc, 16, v10
	v_add_f32_e32 v235, v137, v235
	s_nop 0
	v_cndmask_b32_e32 v8, v8, v235, vcc
	v_add_u32_e32 v10, 2, v17
	v_cmp_gt_u32_e32 vcc, 16, v10
	v_mov_b32_e32 v10, 0xf149f2ca
	v_mov_b32_e32 v11, 0xf149f2ca
	v_add_f32_e32 v236, v138, v236
	s_nop 0
	v_cndmask_b32_e32 v11, v11, v236, vcc
	v_add_u32_e32 v12, 3, v17
	v_cmp_gt_u32_e32 vcc, 16, v12
	v_add_f32_e32 v237, v139, v237
	s_nop 0
	v_cndmask_b32_e32 v10, v10, v237, vcc
	v_add_u32_e32 v12, 8, v17
	v_cmp_gt_u32_e32 vcc, 16, v12
	v_mov_b32_e32 v12, 0xf149f2ca
	v_mov_b32_e32 v13, 0xf149f2ca
	v_add_f32_e32 v238, v140, v238
	s_nop 0
	v_cndmask_b32_e32 v13, v13, v238, vcc
	v_add_u32_e32 v14, 9, v17
	v_cmp_gt_u32_e32 vcc, 16, v14
	v_add_f32_e32 v239, v141, v239
	s_nop 0
	v_cndmask_b32_e32 v12, v12, v239, vcc
	v_add_u32_e32 v14, 10, v17
	v_cmp_gt_u32_e32 vcc, 16, v14
	v_mov_b32_e32 v14, 0xf149f2ca
	v_mov_b32_e32 v15, 0xf149f2ca
	v_add_f32_e32 v240, v142, v240
	s_nop 0
	v_cndmask_b32_e32 v15, v15, v240, vcc
	v_add_u32_e32 v17, 11, v17
	v_cmp_gt_u32_e32 vcc, 16, v17
	v_add_f32_e32 v241, v143, v241
	s_nop 0
	v_cndmask_b32_e32 v14, v14, v241, vcc
	v_max_f32_e32 v16, v0, v0
	v_max_f32_e32 v17, v1, v1
	v_max_f32_e32 v16, v17, v16
	v_max3_f32 v16, v16, v3, v2
	v_max3_f32 v16, v16, v5, v4
	v_max3_f32 v16, v16, v7, v6
	v_max3_f32 v16, v16, v9, v8
	v_max3_f32 v16, v16, v11, v10
	v_max3_f32 v16, v16, v13, v12
	v_max3_f32 v16, v16, v15, v14
	v_mov_b32_e32 v17, v16
	s_nop 1
	v_permlane32_swap_b32_e32 v16, v17
	v_max_f32_e32 v17, v17, v17
	v_max_f32_e32 v16, v16, v16
	v_max_f32_e32 v16, v16, v17
	v_max_f32_e32 v18, v184, v184
	v_sub_f32_e32 v17, v16, v184
	v_max_f32_e32 v16, v18, v16
	v_sub_f32_e32 v18, v184, v16
	v_exp_f32_e32 v18, v18
	v_cmp_ge_f32_e32 vcc, s70, v17
	s_cmp_eq_u64 vcc, exec
	s_cselect_b64 s[6:7], -1, 0
	v_cndmask_b32_e64 v177, v18, 1.0, s[6:7]
	v_cmp_gt_f32_e32 vcc, 1.0, v177
	s_cbranch_vccz .LBB0_357
	s_and_saveexec_b64 s[18:19], s[4:5]
	ds_write_b32 v202, v177 offset:128
	s_or_b64 exec, exec, s[18:19]
	s_waitcnt lgkmcnt(0)
	ds_read_b128 v[18:21], v201 offset:224
	ds_read_b128 v[22:25], v201 offset:192
	ds_read_b128 v[26:29], v201 offset:160
	ds_read_b128 v[30:33], v201 offset:128
	s_waitcnt lgkmcnt(0)
	v_pk_mul_f32 v[126:127], v[126:127], v[20:21]
	v_pk_mul_f32 v[122:123], v[122:123], v[24:25]
	v_pk_mul_f32 v[118:119], v[118:119], v[28:29]
	v_pk_mul_f32 v[114:115], v[114:115], v[32:33]
	v_pk_mul_f32 v[124:125], v[124:125], v[18:19]
	v_pk_mul_f32 v[120:121], v[120:121], v[22:23]
	v_pk_mul_f32 v[116:117], v[116:117], v[26:27]
	v_pk_mul_f32 v[112:113], v[112:113], v[30:31]
	v_pk_mul_f32 v[110:111], v[110:111], v[20:21]
	v_pk_mul_f32 v[106:107], v[106:107], v[24:25]
	v_pk_mul_f32 v[102:103], v[102:103], v[28:29]
	v_pk_mul_f32 v[98:99], v[98:99], v[32:33]
	v_pk_mul_f32 v[108:109], v[108:109], v[18:19]
	v_pk_mul_f32 v[104:105], v[104:105], v[22:23]
	v_pk_mul_f32 v[100:101], v[100:101], v[26:27]
	v_pk_mul_f32 v[96:97], v[96:97], v[30:31]
	v_pk_mul_f32 v[94:95], v[94:95], v[20:21]
	v_pk_mul_f32 v[90:91], v[90:91], v[24:25]
	v_pk_mul_f32 v[86:87], v[86:87], v[28:29]
	v_pk_mul_f32 v[82:83], v[82:83], v[32:33]
	v_pk_mul_f32 v[92:93], v[92:93], v[18:19]
	v_pk_mul_f32 v[88:89], v[88:89], v[22:23]
	v_pk_mul_f32 v[84:85], v[84:85], v[26:27]
	v_pk_mul_f32 v[80:81], v[80:81], v[30:31]
	v_pk_mul_f32 v[78:79], v[78:79], v[20:21]
	v_pk_mul_f32 v[74:75], v[74:75], v[24:25]
	v_pk_mul_f32 v[70:71], v[70:71], v[28:29]
	v_pk_mul_f32 v[66:67], v[66:67], v[32:33]
	v_pk_mul_f32 v[76:77], v[76:77], v[18:19]
	v_pk_mul_f32 v[72:73], v[72:73], v[22:23]
	v_pk_mul_f32 v[68:69], v[68:69], v[26:27]
	v_pk_mul_f32 v[64:65], v[64:65], v[30:31]

.LBB0_361:
	v_cndmask_b32_e64 v178, v16, v184, s[6:7]
	v_sub_f32_e32 v1, v1, v178
	v_sub_f32_e32 v0, v0, v178
	v_sub_f32_e32 v3, v3, v178
	v_sub_f32_e32 v2, v2, v178
	v_sub_f32_e32 v5, v5, v178
	v_sub_f32_e32 v4, v4, v178
	v_sub_f32_e32 v7, v7, v178
	v_sub_f32_e32 v6, v6, v178
	v_exp_f32_e32 v16, v1
	v_exp_f32_e32 v17, v0
	v_exp_f32_e32 v18, v3
	v_exp_f32_e32 v19, v2
	v_exp_f32_e32 v20, v5
	v_exp_f32_e32 v21, v4
	v_exp_f32_e32 v22, v7
	v_exp_f32_e32 v23, v6
	s_add_i32 s6, s81, 0xffff4000
	s_and_b32 s6, s6, 0xc000
	v_sub_f32_e32 v9, v9, v178
	v_sub_f32_e32 v8, v8, v178
	v_sub_f32_e32 v11, v11, v178
	v_sub_f32_e32 v10, v10, v178
	v_sub_f32_e32 v13, v13, v178
	v_sub_f32_e32 v12, v12, v178
	v_sub_f32_e32 v15, v15, v178
	v_sub_f32_e32 v14, v14, v178
	v_add_u32_e32 v24, s6, v217
	v_add_u32_e32 v25, s26, v220
	v_add_u32_e32 v0, v25, v208
	ds_read_b128 v[0:3], v0
	v_add_u32_e32 v4, v25, v209
	ds_read_b128 v[4:7], v4
	v_exp_f32_e32 v26, v9
	v_exp_f32_e32 v27, v8
	v_exp_f32_e32 v31, v12
	v_add_u32_e32 v8, v25, v213
	v_add_u32_e32 v9, v25, v214
	v_add_u32_e32 v12, v25, v215
	s_waitcnt lgkmcnt(0)
	v_mfma_f32_32x32x16_bf16 v[128:143], v[0:3], v[172:175], 0
	v_add_u32_e32 v0, v25, v210
	ds_read_b128 v[0:3], v0
	v_exp_f32_e32 v28, v11
	v_exp_f32_e32 v29, v10
	v_exp_f32_e32 v30, v13
	v_exp_f32_e32 v32, v15
	v_exp_f32_e32 v33, v14
	v_mfma_f32_32x32x16_bf16 v[128:143], v[4:7], v[168:171], v[128:143]
	v_add_u32_e32 v4, v25, v211
	ds_read_b128 v[4:7], v4
	s_waitcnt lgkmcnt(0)
	v_mfma_f32_32x32x16_bf16 v[128:143], v[0:3], v[164:167], v[128:143]
	v_add_f32_e32 v0, 0, v16
	v_add_u32_e32 v1, v25, v212
	v_add_f32_e32 v25, v17, v0
	ds_read_b128 v[0:3], v1
	v_add_f32_e32 v25, v18, v25
	v_mfma_f32_32x32x16_bf16 v[128:143], v[4:7], v[160:163], v[128:143]
	ds_read_b128 v[4:7], v8
	ds_read_b128 v[8:11], v9
	ds_read_b128 v[12:15], v12
	v_cvt_pk_bf16_f32 v48, v16, v17
	v_cvt_pk_bf16_f32 v49, v18, v19
	v_cvt_pk_bf16_f32 v50, v20, v21
	v_cvt_pk_bf16_f32 v51, v22, v23
	v_cvt_pk_bf16_f32 v224, v26, v27
	v_cvt_pk_bf16_f32 v225, v28, v29
	s_waitcnt lgkmcnt(0)
	v_mfma_f32_32x32x16_bf16 v[128:143], v[0:3], v[156:159], v[128:143]
	v_add_f32_e32 v0, v19, v25
	v_add_f32_e32 v0, v20, v0
	v_add_f32_e32 v0, v21, v0
	v_add_f32_e32 v0, v22, v0
	v_add_f32_e32 v0, v23, v0
	v_add_f32_e32 v0, v26, v0
	v_add_f32_e32 v0, v27, v0
	v_mfma_f32_32x32x16_bf16 v[128:143], v[4:7], v[152:155], v[128:143]
	v_add_f32_e32 v0, v28, v0
	v_add_f32_e32 v0, v29, v0
	v_add_f32_e32 v0, v30, v0
	v_add_f32_e32 v0, v31, v0
	v_add_f32_e32 v0, v32, v0
	v_add_f32_e32 v179, v33, v0
	v_mov_b32_e32 v180, v179
	v_mfma_f32_32x32x16_bf16 v[128:143], v[8:11], v[148:151], v[128:143]
	v_permlane32_swap_b32_e32 v48, v50
	v_permlane32_swap_b32_e32 v49, v51
	v_permlane32_swap_b32_e32 v179, v180
	v_cvt_pk_bf16_f32 v226, v30, v31
	v_mfma_f32_32x32x16_bf16 v[128:143], v[12:15], v[144:147], v[128:143]
	v_cvt_pk_bf16_f32 v227, v32, v33
	v_permlane32_swap_b32_e32 v224, v226
	v_permlane32_swap_b32_e32 v225, v227
	v_add_u32_e32 v40, v24, v198
	ds_read_b64_tr_b16 v[0:1], v40 offset:0
	ds_read_b64_tr_b16 v[2:3], v40 offset:0x800
	v_add_u32_e32 v41, s22, v24
	ds_read_b64_tr_b16 v[16:17], v41 offset:0
	ds_read_b64_tr_b16 v[18:19], v41 offset:0x800
	s_waitcnt lgkmcnt(0)
	v_mfma_f32_32x32x16_bf16 v[112:127], v[48:51], v[0:3], v[112:127]
	ds_read_b64_tr_b16 v[20:21], v40 offset:0x200
	ds_read_b64_tr_b16 v[22:23], v40 offset:0xa00
	ds_read_b64_tr_b16 v[32:33], v41 offset:0x200
	ds_read_b64_tr_b16 v[34:35], v41 offset:0xa00
	s_waitcnt lgkmcnt(0)
	s_nop 11
	v_mov_b64_e32 v[0:1], v[112:113]
	v_mov_b64_e32 v[2:3], v[114:115]
	v_mov_b64_e32 v[4:5], v[116:117]
	v_mov_b64_e32 v[6:7], v[118:119]
	v_mov_b64_e32 v[8:9], v[120:121]
	v_mov_b64_e32 v[10:11], v[122:123]
	v_mov_b64_e32 v[12:13], v[124:125]
	v_mov_b64_e32 v[14:15], v[126:127]
	s_nop 1
	v_mfma_f32_32x32x16_bf16 v[0:15], v[224:227], v[16:19], v[0:15]
	v_mfma_f32_32x32x16_bf16 v[96:111], v[48:51], v[20:23], v[96:111]
	ds_read_b64_tr_b16 v[36:37], v40 offset:0x400
	ds_read_b64_tr_b16 v[38:39], v40 offset:0xc00
	ds_read_b64_tr_b16 v[52:53], v41 offset:0x400
	ds_read_b64_tr_b16 v[54:55], v41 offset:0xc00
	s_waitcnt lgkmcnt(0)
	s_nop 11
	v_mov_b64_e32 v[16:17], v[96:97]
	v_mov_b64_e32 v[18:19], v[98:99]
	v_mov_b64_e32 v[20:21], v[100:101]
	v_mov_b64_e32 v[22:23], v[102:103]
	v_mov_b64_e32 v[24:25], v[104:105]
	v_mov_b64_e32 v[26:27], v[106:107]
	v_mov_b64_e32 v[28:29], v[108:109]
	v_mov_b64_e32 v[30:31], v[110:111]
	s_nop 1
	v_mfma_f32_32x32x16_bf16 v[16:31], v[224:227], v[32:35], v[16:31]
	v_mfma_f32_32x32x16_bf16 v[80:95], v[48:51], v[36:39], v[80:95]
	ds_read_b64_tr_b16 v[56:57], v40 offset:0x600
	ds_read_b64_tr_b16 v[58:59], v40 offset:0xe00
	ds_read_b64_tr_b16 v[96:97], v41 offset:0x600
	ds_read_b64_tr_b16 v[98:99], v41 offset:0xe00
	s_waitcnt lgkmcnt(0)
	s_nop 11
	v_mov_b64_e32 v[32:33], v[80:81]
	v_mov_b64_e32 v[34:35], v[82:83]
	v_mov_b64_e32 v[36:37], v[84:85]
	v_mov_b64_e32 v[38:39], v[86:87]
	v_mov_b64_e32 v[40:41], v[88:89]
	v_mov_b64_e32 v[42:43], v[90:91]
	v_mov_b64_e32 v[44:45], v[92:93]
	v_mov_b64_e32 v[46:47], v[94:95]
	s_nop 1
	v_mfma_f32_32x32x16_bf16 v[32:47], v[224:227], v[52:55], v[32:47]
	v_mfma_f32_32x32x16_bf16 v[64:79], v[48:51], v[56:59], v[64:79]
	v_mov_b32_e32 v80, v203
	v_mov_b32_e32 v81, v200
	s_nop 0
	v_add_u32_e32 v52, -4, v80
	v_min_i32_e32 v52, s76, v52
	v_cmp_lt_i32_e32 vcc, 3, v80
	s_nop 1
	v_cndmask_b32_e32 v82, 0, v52, vcc
	s_nop 2
	v_mov_b64_e32 v[48:49], v[64:65]
	v_mov_b64_e32 v[50:51], v[66:67]
	v_mov_b64_e32 v[52:53], v[68:69]
	v_mov_b64_e32 v[54:55], v[70:71]
	v_mov_b64_e32 v[56:57], v[72:73]
	v_mov_b64_e32 v[58:59], v[74:75]
	v_mov_b64_e32 v[60:61], v[76:77]
	v_mov_b64_e32 v[62:63], v[78:79]
	v_add_u32_e32 v65, 8, v82
	v_min_i32_e32 v65, s75, v65
	v_mfma_f32_32x32x16_bf16 v[48:63], v[224:227], v[96:99], v[48:63]
	v_cmp_lt_i32_e64 s[6:7], s23, v65
	v_sub_u32_e32 v65, s23, v80
	v_med3_i32 v64, v81, 8, 56
	v_med3_i32 v65, v65, -7, 7
	v_sub_u32_e32 v66, v206, v81
	v_add_u32_e32 v64, -8, v64
	v_cmp_ge_i32_e32 vcc, s23, v82
	v_lshl_add_u32 v65, v65, 9, s57
	v_lshlrev_b32_e32 v66, 2, v66
	v_add3_u32 v65, v65, v66, v176
	ds_read_b32 v234, v65 offset:3836
	ds_read_b32 v235, v65 offset:3840
	ds_read_b32 v236, v65 offset:3844
	ds_read_b32 v237, v65 offset:3848
	ds_read_b32 v238, v65 offset:3868
	ds_read_b32 v239, v65 offset:3872
	ds_read_b32 v240, v65 offset:3876
	ds_read_b32 v241, v65 offset:3880
	v_sub_u32_e32 v66, v207, v64
	s_and_b64 vcc, s[6:7], vcc
	v_cndmask_b32_e32 v66, v196, v66, vcc
	v_cmp_gt_u32_e64 s[6:7], 16, v66
	v_mov_b32_e32 v72, 0xf149f2ca
	v_mov_b32_e32 v73, 0xf149f2ca
	s_waitcnt lgkmcnt(0)
	v_add_f32_e32 v234, v128, v234
	s_nop 0
	v_cndmask_b32_e64 v73, v73, v234, s[6:7]
	v_add_u32_e32 v67, 1, v66
	v_cmp_gt_u32_e64 s[6:7], 16, v67
	v_add_f32_e32 v235, v129, v235
	s_nop 0
	v_cndmask_b32_e64 v72, v72, v235, s[6:7]
	v_add_u32_e32 v67, 2, v66
	v_cmp_gt_u32_e64 s[6:7], 16, v67
	v_mov_b32_e32 v74, 0xf149f2ca
	v_mov_b32_e32 v75, 0xf149f2ca
	v_add_f32_e32 v236, v130, v236
	s_nop 0
	v_cndmask_b32_e64 v75, v75, v236, s[6:7]
	v_add_u32_e32 v67, 3, v66
	v_cmp_gt_u32_e64 s[6:7], 16, v67
	v_add_f32_e32 v237, v131, v237
	s_nop 0
	v_cndmask_b32_e64 v74, v74, v237, s[6:7]
	v_add_u32_e32 v67, 8, v66
	v_cmp_gt_u32_e64 s[6:7], 16, v67
	v_mov_b32_e32 v76, 0xf149f2ca
	v_mov_b32_e32 v77, 0xf149f2ca
	v_add_f32_e32 v238, v132, v238
	s_nop 0
	v_cndmask_b32_e64 v77, v77, v238, s[6:7]
	v_add_u32_e32 v67, 9, v66
	v_cmp_gt_u32_e64 s[6:7], 16, v67
	v_add_f32_e32 v239, v133, v239
	s_nop 0
	v_cndmask_b32_e64 v76, v76, v239, s[6:7]
	v_add_u32_e32 v67, 10, v66
	v_cmp_gt_u32_e64 s[6:7], 16, v67
	v_mov_b32_e32 v78, 0xf149f2ca
	v_mov_b32_e32 v79, 0xf149f2ca
	v_add_f32_e32 v240, v134, v240
	s_nop 0
	v_cndmask_b32_e64 v79, v79, v240, s[6:7]
	v_add_u32_e32 v66, 11, v66
	v_cmp_gt_u32_e64 s[6:7], 16, v66
	v_add_f32_e32 v241, v135, v241
	s_nop 0
	v_cndmask_b32_e64 v78, v78, v241, s[6:7]
	v_sub_u32_e32 v64, v205, v64
	v_cndmask_b32_e32 v81, v196, v64, vcc
	v_lshl_add_u32 v80, v218, 2, v65
	ds_read_b32 v234, v80 offset:3836
	ds_read_b32 v235, v80 offset:3840
	ds_read_b32 v236, v80 offset:3844
	ds_read_b32 v237, v80 offset:3848
	ds_read_b32 v238, v80 offset:3868
	ds_read_b32 v239, v80 offset:3872
	ds_read_b32 v240, v80 offset:3876
	ds_read_b32 v241, v80 offset:3880
	v_cmp_gt_u32_e32 vcc, 16, v81
	v_mov_b32_e32 v65, 0xf149f2ca
	v_mov_b32_e32 v64, 0xf149f2ca
	s_waitcnt lgkmcnt(0)
	v_add_f32_e32 v234, v136, v234
	s_nop 0
	v_cndmask_b32_e32 v64, v64, v234, vcc
	v_add_u32_e32 v66, 1, v81
	v_cmp_gt_u32_e32 vcc, 16, v66
	v_add_f32_e32 v235, v137, v235
	s_nop 0
	v_cndmask_b32_e32 v65, v65, v235, vcc
	v_add_u32_e32 v66, 2, v81
	v_cmp_gt_u32_e32 vcc, 16, v66
	v_mov_b32_e32 v67, 0xf149f2ca
	v_mov_b32_e32 v66, 0xf149f2ca
	v_add_f32_e32 v236, v138, v236
	s_nop 0
	v_cndmask_b32_e32 v66, v66, v236, vcc
	v_add_u32_e32 v68, 3, v81
	v_cmp_gt_u32_e32 vcc, 16, v68
	v_add_f32_e32 v237, v139, v237
	s_nop 0
	v_cndmask_b32_e32 v67, v67, v237, vcc
	v_add_u32_e32 v68, 8, v81
	v_cmp_gt_u32_e32 vcc, 16, v68
	v_mov_b32_e32 v69, 0xf149f2ca
	v_mov_b32_e32 v68, 0xf149f2ca
	v_add_f32_e32 v238, v140, v238
	s_nop 0
	v_cndmask_b32_e32 v68, v68, v238, vcc
	v_add_u32_e32 v70, 9, v81
	v_cmp_gt_u32_e32 vcc, 16, v70
	v_add_f32_e32 v239, v141, v239
	s_nop 0
	v_cndmask_b32_e32 v69, v69, v239, vcc
	v_add_u32_e32 v70, 10, v81
	v_cmp_gt_u32_e32 vcc, 16, v70
	v_mov_b32_e32 v71, 0xf149f2ca
	v_mov_b32_e32 v70, 0xf149f2ca
	v_add_f32_e32 v240, v142, v240
	s_nop 0
	v_cndmask_b32_e32 v70, v70, v240, vcc
	v_add_u32_e32 v81, 11, v81
	v_cmp_gt_u32_e32 vcc, 16, v81
	v_add_f32_e32 v241, v143, v241
	s_nop 0
	v_cndmask_b32_e32 v71, v71, v241, vcc
	v_max_f32_e32 v80, v72, v72
	v_max_f32_e32 v81, v73, v73
	v_max_f32_e32 v80, v81, v80
	v_max3_f32 v80, v80, v75, v74
	v_max3_f32 v80, v80, v77, v76
	v_max3_f32 v80, v80, v79, v78
	v_max3_f32 v80, v80, v64, v65
	v_max3_f32 v80, v80, v66, v67
	v_max3_f32 v80, v80, v68, v69
	v_max3_f32 v80, v80, v70, v71
	v_mov_b32_e32 v81, v80
	s_nop 1
	v_permlane32_swap_b32_e32 v80, v81
	v_max_f32_e32 v81, v81, v81
	v_max_f32_e32 v80, v80, v80
	v_max_f32_e32 v80, v80, v81
	v_max_f32_e32 v82, v178, v178
	v_sub_f32_e32 v81, v80, v178
	v_max_f32_e32 v80, v82, v80
	v_sub_f32_e32 v82, v178, v80
	v_exp_f32_e32 v82, v82
	v_cmp_ge_f32_e32 vcc, s70, v81
	s_cmp_eq_u64 vcc, exec
	s_cselect_b64 s[6:7], -1, 0
	v_cndmask_b32_e64 v88, v82, 1.0, s[6:7]
	v_cmp_gt_f32_e32 vcc, 1.0, v88
	s_cbranch_vccz .LBB0_397
	s_and_saveexec_b64 s[20:21], s[4:5]
	ds_write_b32 v202, v88 offset:128
	s_or_b64 exec, exec, s[20:21]
	s_waitcnt lgkmcnt(0)
	ds_read_b128 v[82:85], v201 offset:224
	ds_read_b128 v[90:93], v201 offset:192
	ds_read_b128 v[94:97], v201 offset:160
	ds_read_b128 v[98:101], v201 offset:128
	s_waitcnt lgkmcnt(0)
	v_pk_mul_f32 v[14:15], v[14:15], v[84:85]
	v_pk_mul_f32 v[10:11], v[10:11], v[92:93]
	v_pk_mul_f32 v[6:7], v[6:7], v[96:97]
	v_pk_mul_f32 v[2:3], v[2:3], v[100:101]
	v_pk_mul_f32 v[12:13], v[12:13], v[82:83]
	v_pk_mul_f32 v[8:9], v[8:9], v[90:91]
	v_pk_mul_f32 v[4:5], v[4:5], v[94:95]
	v_pk_mul_f32 v[0:1], v[0:1], v[98:99]
	v_pk_mul_f32 v[30:31], v[30:31], v[84:85]
	v_pk_mul_f32 v[26:27], v[26:27], v[92:93]
	v_pk_mul_f32 v[22:23], v[22:23], v[96:97]
	v_pk_mul_f32 v[18:19], v[18:19], v[100:101]
	v_pk_mul_f32 v[28:29], v[28:29], v[82:83]
	v_pk_mul_f32 v[24:25], v[24:25], v[90:91]
	v_pk_mul_f32 v[20:21], v[20:21], v[94:95]
	v_pk_mul_f32 v[16:17], v[16:17], v[98:99]
	v_pk_mul_f32 v[46:47], v[46:47], v[84:85]
	v_pk_mul_f32 v[42:43], v[42:43], v[92:93]
	v_pk_mul_f32 v[38:39], v[38:39], v[96:97]
	v_pk_mul_f32 v[34:35], v[34:35], v[100:101]
	v_pk_mul_f32 v[44:45], v[44:45], v[82:83]
	v_pk_mul_f32 v[40:41], v[40:41], v[90:91]
	v_pk_mul_f32 v[36:37], v[36:37], v[94:95]
	v_pk_mul_f32 v[32:33], v[32:33], v[98:99]
	v_pk_mul_f32 v[62:63], v[62:63], v[84:85]
	v_pk_mul_f32 v[58:59], v[58:59], v[92:93]
	v_pk_mul_f32 v[54:55], v[54:55], v[96:97]
	v_pk_mul_f32 v[50:51], v[50:51], v[100:101]
	v_pk_mul_f32 v[60:61], v[60:61], v[82:83]
	v_pk_mul_f32 v[56:57], v[56:57], v[90:91]
	v_pk_mul_f32 v[52:53], v[52:53], v[94:95]
	v_pk_mul_f32 v[48:49], v[48:49], v[98:99]

.LBB0_399:
	s_waitcnt vmcnt(0) lgkmcnt(0)
	s_barrier
	s_add_i32 s6, 0, 0x8000
	v_add_u32_e32 v97, s6, v199
	s_add_i32 s58, 0, 0x18000
	v_add_u32_e32 v106, s58, v219
	v_add_u32_e32 v64, v106, v208
	ds_read_b128 v[64:67], v64
	v_add_u32_e32 v68, v106, v209
	ds_read_b128 v[98:101], v68
	v_exp_f32_e32 v110, v80
	v_add_u32_e32 v80, v106, v210
	ds_read_b128 v[102:105], v80
	v_exp_f32_e32 v114, v84
	v_add_f32_e32 v84, 0, v95
	v_exp_f32_e32 v115, v85
	s_waitcnt lgkmcnt(0)
	v_mfma_f32_32x32x16_bf16 v[64:79], v[64:67], v[172:175], 0
	v_exp_f32_e32 v116, v86
	v_exp_f32_e32 v117, v87
	v_exp_f32_e32 v111, v81
	v_exp_f32_e32 v112, v82
	v_exp_f32_e32 v113, v83
	v_mfma_f32_32x32x16_bf16 v[64:79], v[98:101], v[168:171], v[64:79]
	v_add_f32_e32 v98, v96, v84
	v_add_u32_e32 v84, v106, v212
	ds_read_b128 v[84:87], v84
	v_add_u32_e32 v80, v106, v211
	ds_read_b128 v[80:83], v80
	v_add_u32_e32 v99, v106, v213
	v_add_u32_e32 v100, v106, v214
	v_mfma_f32_32x32x16_bf16 v[64:79], v[102:105], v[164:167], v[64:79]
	v_add_u32_e32 v102, v106, v215
	v_add_f32_e32 v106, v94, v98
	v_add_f32_e32 v118, v93, v106
	s_waitcnt lgkmcnt(0)
	v_mfma_f32_32x32x16_bf16 v[64:79], v[80:83], v[160:163], v[64:79]
	ds_read_b128 v[80:83], v99
	ds_read_b128 v[98:101], v100
	ds_read_b128 v[102:105], v102
	v_cvt_pk_bf16_f32 v106, v95, v96
	v_cvt_pk_bf16_f32 v107, v94, v93
	v_cvt_pk_bf16_f32 v108, v92, v89
	v_cvt_pk_bf16_f32 v109, v90, v91
	s_nop 0
	v_permlane32_swap_b32_e32 v106, v108
	v_mfma_f32_32x32x16_bf16 v[64:79], v[84:87], v[156:159], v[64:79]
	v_add_f32_e32 v84, v92, v118
	v_permlane32_swap_b32_e32 v107, v109
	s_waitcnt lgkmcnt(0)
	v_mfma_f32_32x32x16_bf16 v[64:79], v[80:83], v[152:155], v[64:79]
	v_add_f32_e32 v80, v89, v84
	v_add_f32_e32 v80, v90, v80
	v_add_f32_e32 v80, v91, v80
	v_add_f32_e32 v80, v110, v80
	v_add_f32_e32 v80, v111, v80
	v_add_f32_e32 v80, v112, v80
	v_add_f32_e32 v80, v113, v80
	v_mfma_f32_32x32x16_bf16 v[64:79], v[98:101], v[148:151], v[64:79]
	v_add_f32_e32 v80, v114, v80
	v_add_f32_e32 v80, v115, v80
	v_add_f32_e32 v80, v116, v80
	v_add_f32_e32 v80, v117, v80
	v_mov_b32_e32 v81, v80
	s_nop 1
	v_permlane32_swap_b32_e32 v80, v81
	v_mfma_f32_32x32x16_bf16 v[64:79], v[102:105], v[144:147], v[64:79]
	v_cvt_pk_bf16_f32 v90, v110, v111
	v_cvt_pk_bf16_f32 v91, v112, v113
	v_cvt_pk_bf16_f32 v92, v114, v115
	v_cvt_pk_bf16_f32 v93, v116, v117
	s_nop 0
	v_permlane32_swap_b32_e32 v90, v92
	v_permlane32_swap_b32_e32 v91, v93
	v_add_u32_e32 v86, v97, v198
	ds_read_b64_tr_b16 v[82:83], v86 offset:0
	ds_read_b64_tr_b16 v[84:85], v86 offset:0x800
	v_add_u32_e32 v87, s22, v97
	ds_read_b64_tr_b16 v[94:95], v87 offset:0
	ds_read_b64_tr_b16 v[96:97], v87 offset:0x800
	s_waitcnt lgkmcnt(0)
	v_mfma_f32_32x32x16_bf16 v[0:15], v[106:109], v[82:85], v[0:15]
	ds_read_b64_tr_b16 v[82:83], v86 offset:0x200
	ds_read_b64_tr_b16 v[84:85], v86 offset:0xa00
	ds_read_b64_tr_b16 v[98:99], v87 offset:0x200
	ds_read_b64_tr_b16 v[100:101], v87 offset:0xa00
	s_waitcnt lgkmcnt(0)
	v_mfma_f32_32x32x16_bf16 v[0:15], v[90:93], v[94:97], v[0:15]
	v_mfma_f32_32x32x16_bf16 v[16:31], v[106:109], v[82:85], v[16:31]
	ds_read_b64_tr_b16 v[82:83], v86 offset:0x400
	ds_read_b64_tr_b16 v[84:85], v86 offset:0xc00
	ds_read_b64_tr_b16 v[94:95], v87 offset:0x400
	ds_read_b64_tr_b16 v[96:97], v87 offset:0xc00
	s_waitcnt lgkmcnt(0)
	v_mfma_f32_32x32x16_bf16 v[16:31], v[90:93], v[98:101], v[16:31]
	v_mfma_f32_32x32x16_bf16 v[32:47], v[106:109], v[82:85], v[32:47]
	ds_read_b64_tr_b16 v[82:83], v86 offset:0x600
	ds_read_b64_tr_b16 v[84:85], v86 offset:0xe00
	ds_read_b64_tr_b16 v[98:99], v87 offset:0x600
	ds_read_b64_tr_b16 v[100:101], v87 offset:0xe00
	s_waitcnt lgkmcnt(0)
	v_mfma_f32_32x32x16_bf16 v[32:47], v[90:93], v[94:97], v[32:47]
	v_mfma_f32_32x32x16_bf16 v[48:63], v[106:109], v[82:85], v[48:63]
	s_add_i32 s77, s77, 10
	v_add_u32_e32 v86, -4, v203
	v_min_i32_e32 v86, s76, v86
	v_cmp_lt_i32_e32 vcc, 3, v203
	v_med3_i32 v82, v200, 8, 56
	v_sub_u32_e32 v84, 8, v82
	v_mfma_f32_32x32x16_bf16 v[48:63], v[90:93], v[98:101], v[48:63]
	v_cndmask_b32_e32 v86, 0, v86, vcc
	s_cmp_lt_i32 s77, s75
	v_sub_u32_e32 v82, s77, v203
	s_cselect_b64 s[18:19], -1, 0
	v_cmp_lt_i32_e64 s[6:7], s78, v86
	v_med3_i32 v82, v82, -7, 7
	v_sub_u32_e32 v83, v206, v200
	v_cmp_ge_i32_e32 vcc, s77, v86
	s_and_b64 s[6:7], s[18:19], s[6:7]
	v_lshl_add_u32 v82, v82, 9, s57
	v_lshlrev_b32_e32 v83, 2, v83
	v_add3_u32 v85, v82, v83, v176
	ds_read_b32 v234, v85 offset:3836
	ds_read_b32 v235, v85 offset:3840
	ds_read_b32 v236, v85 offset:3844
	ds_read_b32 v237, v85 offset:3848
	ds_read_b32 v238, v85 offset:3868
	ds_read_b32 v239, v85 offset:3872
	ds_read_b32 v240, v85 offset:3876
	ds_read_b32 v241, v85 offset:3880
	v_add_u32_e32 v82, v84, v207
	s_and_b64 vcc, s[6:7], vcc
	v_cndmask_b32_e32 v86, v196, v82, vcc
	v_cmp_gt_u32_e64 s[6:7], 16, v86
	v_mov_b32_e32 v82, 0xf149f2ca
	v_mov_b32_e32 v83, 0xf149f2ca
	s_waitcnt lgkmcnt(0)
	v_add_f32_e32 v234, v64, v234
	s_nop 0
	v_cndmask_b32_e64 v83, v83, v234, s[6:7]
	v_add_u32_e32 v64, 1, v86
	v_cmp_gt_u32_e64 s[6:7], 16, v64
	v_add_f32_e32 v235, v65, v235
	s_nop 0
	v_cndmask_b32_e64 v82, v82, v235, s[6:7]
	v_add_u32_e32 v64, 2, v86
	v_cmp_gt_u32_e64 s[6:7], 16, v64
	v_mov_b32_e32 v64, 0xf149f2ca
	v_mov_b32_e32 v65, 0xf149f2ca
	v_add_f32_e32 v236, v66, v236
	s_nop 0
	v_cndmask_b32_e64 v65, v65, v236, s[6:7]
	v_add_u32_e32 v66, 3, v86
	v_cmp_gt_u32_e64 s[6:7], 16, v66
	v_add_f32_e32 v237, v67, v237
	s_nop 0
	v_cndmask_b32_e64 v64, v64, v237, s[6:7]
	v_add_u32_e32 v66, 8, v86
	v_cmp_gt_u32_e64 s[6:7], 16, v66
	v_mov_b32_e32 v66, 0xf149f2ca
	v_mov_b32_e32 v67, 0xf149f2ca
	v_add_f32_e32 v238, v68, v238
	s_nop 0
	v_cndmask_b32_e64 v67, v67, v238, s[6:7]
	v_add_u32_e32 v68, 9, v86
	v_cmp_gt_u32_e64 s[6:7], 16, v68
	v_add_f32_e32 v239, v69, v239
	s_nop 0
	v_cndmask_b32_e64 v66, v66, v239, s[6:7]
	v_add_u32_e32 v68, 10, v86
	v_cmp_gt_u32_e64 s[6:7], 16, v68
	v_mov_b32_e32 v68, 0xf149f2ca
	v_mov_b32_e32 v69, 0xf149f2ca
	v_add_f32_e32 v240, v70, v240
	s_nop 0
	v_cndmask_b32_e64 v69, v69, v240, s[6:7]
	v_add_u32_e32 v70, 11, v86
	v_cmp_gt_u32_e64 s[6:7], 16, v70
	v_add_f32_e32 v241, v71, v241
	s_nop 0
	v_cndmask_b32_e64 v68, v68, v241, s[6:7]
	v_add_u32_e32 v71, v84, v205
	v_lshlrev_b32_e32 v70, 6, v204
	v_cndmask_b32_e32 v86, v196, v71, vcc
	v_cmp_gt_u32_e32 vcc, 16, v86
	v_mov_b32_e32 v71, 0xf149f2ca
	v_add_u32_e32 v70, v85, v70
	ds_read_b32 v234, v70 offset:3836
	ds_read_b32 v235, v70 offset:3840
	ds_read_b32 v236, v70 offset:3844
	ds_read_b32 v237, v70 offset:3848
	ds_read_b32 v238, v70 offset:3868
	ds_read_b32 v239, v70 offset:3872
	ds_read_b32 v240, v70 offset:3876
	ds_read_b32 v241, v70 offset:3880
	v_mov_b32_e32 v84, 0xf149f2ca
	s_waitcnt lgkmcnt(0)
	v_add_f32_e32 v234, v72, v234
	s_nop 0
	v_cndmask_b32_e32 v84, v84, v234, vcc
	v_add_u32_e32 v72, 1, v86
	v_cmp_gt_u32_e32 vcc, 16, v72
	v_add_f32_e32 v235, v73, v235
	s_nop 0
	v_cndmask_b32_e32 v71, v71, v235, vcc
	v_add_u32_e32 v72, 2, v86
	v_cmp_gt_u32_e32 vcc, 16, v72
	v_mov_b32_e32 v72, 0xf149f2ca
	v_mov_b32_e32 v73, 0xf149f2ca
	v_add_f32_e32 v236, v74, v236
	s_nop 0
	v_cndmask_b32_e32 v73, v73, v236, vcc
	v_add_u32_e32 v74, 3, v86
	v_cmp_gt_u32_e32 vcc, 16, v74
	v_add_f32_e32 v237, v75, v237
	s_nop 0
	v_cndmask_b32_e32 v72, v72, v237, vcc
	v_add_u32_e32 v74, 8, v86
	v_cmp_gt_u32_e32 vcc, 16, v74
	v_mov_b32_e32 v74, 0xf149f2ca
	v_mov_b32_e32 v75, 0xf149f2ca
	v_add_f32_e32 v238, v76, v238
	s_nop 0
	v_cndmask_b32_e32 v75, v75, v238, vcc
	v_add_u32_e32 v76, 9, v86
	v_cmp_gt_u32_e32 vcc, 16, v76
	v_add_f32_e32 v239, v77, v239
	s_nop 0
	v_cndmask_b32_e32 v74, v74, v239, vcc
	v_add_u32_e32 v76, 10, v86
	v_cmp_gt_u32_e32 vcc, 16, v76
	v_mov_b32_e32 v76, 0xf149f2ca
	v_mov_b32_e32 v77, 0xf149f2ca
	v_add_f32_e32 v240, v78, v240
	s_nop 0
	v_cndmask_b32_e32 v77, v77, v240, vcc
	v_add_u32_e32 v78, 11, v86
	v_cmp_gt_u32_e32 vcc, 16, v78
	v_add_f32_e32 v241, v79, v241
	s_nop 0
	v_cndmask_b32_e32 v76, v76, v241, vcc
	v_max_f32_e32 v70, v82, v82
	v_max_f32_e32 v78, v83, v83
	v_max_f32_e32 v70, v78, v70
	v_max3_f32 v70, v70, v65, v64
	v_max3_f32 v70, v70, v67, v66
	v_max3_f32 v70, v70, v69, v68
	v_max3_f32 v70, v70, v84, v71
	v_max3_f32 v70, v70, v73, v72
	v_max3_f32 v70, v70, v75, v74
	v_max3_f32 v70, v70, v77, v76
	v_mov_b32_e32 v78, v70
	s_nop 1
	v_permlane32_swap_b32_e32 v70, v78
	v_max_f32_e32 v78, v78, v78
	v_max_f32_e32 v70, v70, v70
	v_max_f32_e32 v70, v70, v78
	v_max_f32_e32 v78, v184, v184
	v_max_f32_e32 v78, v78, v70
	v_sub_f32_e32 v79, v70, v184
	v_sub_f32_e32 v70, v184, v78
	v_exp_f32_e32 v70, v70
	v_cmp_ge_f32_e32 vcc, s70, v79
	s_cmp_eq_u64 vcc, exec
	s_cselect_b64 s[6:7], -1, 0
	v_cndmask_b32_e64 v70, v70, 1.0, s[6:7]
	v_cmp_gt_f32_e32 vcc, 1.0, v70
	s_cbranch_vccz .LBB0_435
	s_and_saveexec_b64 s[18:19], s[4:5]
	ds_write_b32 v202, v70 offset:128
	s_or_b64 exec, exec, s[18:19]
	s_waitcnt lgkmcnt(0)
	ds_read_b128 v[90:93], v201 offset:224
	ds_read_b128 v[94:97], v201 offset:192
	ds_read_b128 v[98:101], v201 offset:160
	ds_read_b128 v[102:105], v201 offset:128
	s_waitcnt lgkmcnt(0)
	v_pk_mul_f32 v[14:15], v[14:15], v[92:93]
	v_pk_mul_f32 v[10:11], v[10:11], v[96:97]
	v_pk_mul_f32 v[6:7], v[6:7], v[100:101]
	v_pk_mul_f32 v[2:3], v[2:3], v[104:105]
	v_pk_mul_f32 v[12:13], v[12:13], v[90:91]
	v_pk_mul_f32 v[8:9], v[8:9], v[94:95]
	v_pk_mul_f32 v[4:5], v[4:5], v[98:99]
	v_pk_mul_f32 v[0:1], v[0:1], v[102:103]
	v_pk_mul_f32 v[30:31], v[30:31], v[92:93]
	v_pk_mul_f32 v[26:27], v[26:27], v[96:97]
	v_pk_mul_f32 v[22:23], v[22:23], v[100:101]
	v_pk_mul_f32 v[18:19], v[18:19], v[104:105]
	v_pk_mul_f32 v[28:29], v[28:29], v[90:91]
	v_pk_mul_f32 v[24:25], v[24:25], v[94:95]
	v_pk_mul_f32 v[20:21], v[20:21], v[98:99]
	v_pk_mul_f32 v[16:17], v[16:17], v[102:103]
	v_pk_mul_f32 v[46:47], v[46:47], v[92:93]
	v_pk_mul_f32 v[42:43], v[42:43], v[96:97]
	v_pk_mul_f32 v[38:39], v[38:39], v[100:101]
	v_pk_mul_f32 v[34:35], v[34:35], v[104:105]
	v_pk_mul_f32 v[44:45], v[44:45], v[90:91]
	v_pk_mul_f32 v[40:41], v[40:41], v[94:95]
	v_pk_mul_f32 v[36:37], v[36:37], v[98:99]
	v_pk_mul_f32 v[32:33], v[32:33], v[102:103]
	v_pk_mul_f32 v[62:63], v[62:63], v[92:93]
	v_pk_mul_f32 v[58:59], v[58:59], v[96:97]
	v_pk_mul_f32 v[54:55], v[54:55], v[100:101]
	v_pk_mul_f32 v[50:51], v[50:51], v[104:105]
	v_pk_mul_f32 v[60:61], v[60:61], v[90:91]
	v_pk_mul_f32 v[56:57], v[56:57], v[94:95]
	v_pk_mul_f32 v[52:53], v[52:53], v[98:99]
	v_pk_mul_f32 v[48:49], v[48:49], v[102:103]
